# barrier-4 fast path polls its group counter without s_sleep between polls
# speedup vs baseline: 1.0023x; 1.0002x over previous
.Lgb_spin:
	global_load_dword v2, v0, s[52:53] sc1
	s_waitcnt vmcnt(0)
	v_readfirstlane_b32 s8, v2
	s_cmp_ge_u32 s8, 4
	s_cbranch_scc1 .Lgb_done
	s_add_i32 s9, s9, 1
	s_cmp_lt_u32 s9, 0x40000
	s_cbranch_scc1 .Lgb_spin
